# hgrn_pre: each wave touches the z lines of the workgroup's next hgrn_pre item (one load, one lane per 128-byte line) behind its own loads, so the next item's two serialized load latencies hit L2
# baseline (speedup 1.0000x reference)
.LBB0_413:
	s_lshl_b32 s0, s89, 7
	s_and_b32 s12, s0, 0x380
	s_lshl_b32 s0, s12, 2
	v_lshl_add_u64 v[0:1], v[134:135], 0, s[0:1]
	s_waitcnt lgkmcnt(1)
	v_add_co_u32_e32 v2, vcc, 0x1000, v0
	s_movk_i32 s63, 0x3000
	s_waitcnt lgkmcnt(0)
	v_addc_co_u32_e32 v3, vcc, 0, v1, vcc
	global_load_dwordx2 v[2:3], v[2:3], off
	s_nop 0
	global_load_dwordx2 v[4:5], v[0:1], off
	v_add_co_u32_e32 v252, vcc, 0x3000, v0
	s_nop 1
	v_addc_co_u32_e32 v253, vcc, 0, v1, vcc
	v_add_co_u32_e32 v254, vcc, 0x2000, v0
	s_nop 1
	v_addc_co_u32_e32 v255, vcc, 0, v1, vcc
	global_load_dwordx2 v[252:253], v[252:253], off
	global_load_dwordx2 v[254:255], v[254:255], off
	s_movk_i32 s62, 0x2000
	s_ashr_i32 s56, s89, 9
	v_readfirstlane_b32 s9, v221
	s_bfe_u32 s8, s89, 0x60003
	s_ashr_i32 s57, s56, 31
	s_lshr_b32 s14, s9, 6
	s_lshl_b64 s[18:19], s[56:57], 12
	s_lshl_b32 s13, s8, 6
	s_or_b32 s13, s18, s13
	s_lshl_b32 s15, s14, 3
	s_add_u32 s54, s13, s15
	s_addc_u32 s55, s19, 0
	s_mul_i32 s13, s55, 0x4800
	s_mul_hi_u32 s15, s54, 0x4800
	s_add_i32 s15, s15, s13
	s_mul_i32 s13, s54, 0x4800
	s_add_u32 s13, s82, s13
	s_addc_u32 s15, s83, s15
	s_lshl_b32 s12, s12, 1
	s_add_u32 s58, s13, s12
	s_addc_u32 s59, s15, 0
	v_lshlrev_b32_e32 v128, 1, v132
	s_movk_i32 s13, 0x4000
	global_load_dword v50, v128, s[58:59] nt
	s_cmp_lt_u32 s9, 64
	s_cselect_b64 s[50:51], -1, 0
	s_cmpk_gt_u32 s9, 0x7f
	s_cselect_b64 s[52:53], -1, 0
	s_cmpk_gt_u32 s9, 0xbf
	s_cselect_b64 s[48:49], -1, 0
	s_cmpk_lt_u32 s9, 0x80
	s_cselect_b64 s[46:47], -1, 0
	s_cmpk_gt_u32 s9, 0xff
	s_cselect_b64 s[44:45], -1, 0
	s_cmpk_lt_u32 s9, 0xc0
	s_cselect_b64 s[42:43], -1, 0
	s_cmpk_gt_u32 s9, 0x13f
	s_cselect_b64 s[40:41], -1, 0
	s_cmpk_lt_u32 s9, 0x100
	s_cselect_b64 s[38:39], -1, 0
	s_cmpk_gt_u32 s9, 0x17f
	s_cselect_b64 s[36:37], -1, 0
	s_cmpk_lt_u32 s9, 0x140
	s_cselect_b64 s[34:35], -1, 0
	s_cmpk_gt_u32 s9, 0x1bf
	s_cselect_b64 s[30:31], -1, 0
	s_cmpk_lt_u32 s9, 0x180
	s_cselect_b64 s[28:29], -1, 0
	s_cmpk_gt_u32 s9, 0x1ff
	s_cselect_b64 s[26:27], -1, 0
	s_cmpk_lt_u32 s9, 0x1c0
	s_cselect_b64 s[24:25], -1, 0
	s_movk_i32 s86, 0x2000
	s_movk_i32 s96, 0x3000
	s_waitcnt vmcnt(1)
	v_sub_f32_e32 v2, v2, v4
	v_mul_f32_e32 v4, 0x3fb8aa3b, v2
	v_fma_f32 v6, v2, s11, -v4
	v_rndne_f32_e32 v7, v4
	v_fmac_f32_e32 v6, 0x32a5705f, v2
	v_sub_f32_e32 v4, v4, v7
	v_add_f32_e32 v4, v4, v6
	v_exp_f32_e32 v4, v4
	v_cvt_i32_f32_e32 v6, v7
	v_cmp_ngt_f32_e32 vcc, s16, v2
	v_ldexp_f32 v4, v4, v6
	s_nop 0
	v_cndmask_b32_e32 v4, 0, v4, vcc
	v_cmp_nlt_f32_e32 vcc, s17, v2
	v_sub_f32_e32 v2, v3, v5
	v_mul_f32_e32 v3, 0x3fb8aa3b, v2
	v_cndmask_b32_e32 v52, v222, v4, vcc
	v_fma_f32 v4, v2, s11, -v3
	v_rndne_f32_e32 v5, v3
	v_fmac_f32_e32 v4, 0x32a5705f, v2
	v_sub_f32_e32 v3, v3, v5
	v_add_f32_e32 v3, v3, v4
	v_exp_f32_e32 v3, v3
	v_cvt_i32_f32_e32 v4, v5
	v_cmp_ngt_f32_e32 vcc, s16, v2
	s_waitcnt vmcnt(0)
	v_lshlrev_b32_e32 v66, 16, v50
	v_and_b32_e32 v67, 0xffff0000, v50
	v_ldexp_f32 v3, v3, v4
	v_cndmask_b32_e32 v3, 0, v3, vcc
	v_cmp_nlt_f32_e32 vcc, s17, v2
	v_mul_f32_e32 v50, 0xbfb8aa3b, v66
	v_exp_f32_e32 v50, v50
	v_cndmask_b32_e32 v53, v222, v3, vcc
	v_add_f32_e32 v50, 1.0, v50
	v_rcp_f32_e32 v50, v50
	v_pk_add_f32 v[52:53], v[52:53], 1.0 op_sel_hi:[1,0]
	v_mov_b32_e32 v2, v252
	v_mov_b32_e32 v3, v253
	v_mov_b32_e32 v0, v254
	v_mov_b32_e32 v1, v255
	v_sub_f32_e32 v0, v2, v0
	v_mul_f32_e32 v2, 0x3fb8aa3b, v0
	v_fma_f32 v4, v0, s11, -v2
	v_rndne_f32_e32 v5, v2
	v_fmac_f32_e32 v4, 0x32a5705f, v0
	v_sub_f32_e32 v2, v2, v5
	v_add_f32_e32 v2, v2, v4
	v_exp_f32_e32 v2, v2
	v_cvt_i32_f32_e32 v4, v5
	v_cmp_ngt_f32_e32 vcc, s16, v0
	v_ldexp_f32 v2, v2, v4
	s_nop 0
	v_cndmask_b32_e32 v2, 0, v2, vcc
	v_cmp_nlt_f32_e32 vcc, s17, v0
	v_sub_f32_e32 v0, v3, v1
	v_mul_f32_e32 v1, 0x3fb8aa3b, v0
	v_cndmask_b32_e32 v56, v222, v2, vcc
	v_fma_f32 v2, v0, s11, -v1
	v_rndne_f32_e32 v3, v1
	v_fmac_f32_e32 v2, 0x32a5705f, v0
	v_sub_f32_e32 v1, v1, v3
	v_add_f32_e32 v1, v1, v2
	v_exp_f32_e32 v1, v1
	v_cvt_i32_f32_e32 v2, v3
	v_cmp_ngt_f32_e32 vcc, s16, v0
	v_ldexp_f32 v1, v1, v2
	s_nop 0
	v_cndmask_b32_e32 v1, 0, v1, vcc
	v_cmp_nlt_f32_e32 vcc, s17, v0
	s_nop 1
	v_cndmask_b32_e32 v57, v222, v1, vcc
	v_lshl_add_u64 v[0:1], s[58:59], 0, v[128:129]
	v_add_co_u32_e32 v44, vcc, s7, v0
	v_pk_add_f32 v[56:57], v[56:57], 1.0 op_sel_hi:[1,0]
	s_nop 0
	v_addc_co_u32_e32 v45, vcc, 0, v1, vcc
	global_load_dword v2, v[44:45], off offset:2048 nt
	v_add_co_u32_e32 v42, vcc, s62, v0
	s_nop 1
	v_addc_co_u32_e32 v43, vcc, 0, v1, vcc
	v_add_co_u32_e32 v40, vcc, s13, v0
	s_movk_i32 s13, 0x6000
	s_nop 0
	v_addc_co_u32_e32 v41, vcc, 0, v1, vcc
	v_add_co_u32_e32 v38, vcc, s13, v0
	global_load_dword v46, v[42:43], off nt
	global_load_dword v64, v[40:41], off offset:2048 nt
	v_addc_co_u32_e32 v39, vcc, 0, v1, vcc
	global_load_dword v3, v[38:39], off nt
	global_load_dword v48, v[38:39], off offset:2048 nt
	v_add_co_u32_e32 v36, vcc, s33, v0
	s_mov_b32 s13, 0xa000
	s_nop 0
	v_addc_co_u32_e32 v37, vcc, 0, v1, vcc
	v_add_co_u32_e32 v34, vcc, s13, v0
	global_load_dword v72, v[36:37], off nt
	s_nop 0
	v_addc_co_u32_e32 v35, vcc, 0, v1, vcc
	global_load_dword v4, v[34:35], off offset:2048 nt
	s_mov_b32 s13, 0xb000
	v_add_co_u32_e32 v30, vcc, s13, v0
	s_mov_b32 s13, 0xd000
	s_nop 0
	v_addc_co_u32_e32 v31, vcc, 0, v1, vcc
	v_add_co_u32_e32 v32, vcc, s13, v0
	s_mov_b32 s13, 0xf000
	s_nop 0
	v_addc_co_u32_e32 v33, vcc, 0, v1, vcc
	v_add_co_u32_e32 v28, vcc, s13, v0
	global_load_dword v49, v[30:31], off nt
	global_load_dword v80, v[32:33], off offset:2048 nt
	v_addc_co_u32_e32 v29, vcc, 0, v1, vcc
	global_load_dword v5, v[28:29], off nt
	global_load_dword v51, v[28:29], off offset:2048 nt
	s_mov_b32 s13, 0x12000
	v_add_co_u32_e32 v26, vcc, s13, v0
	s_mov_b32 s13, 0x13000
	s_nop 0
	v_addc_co_u32_e32 v27, vcc, 0, v1, vcc
	v_add_co_u32_e32 v24, vcc, s13, v0
	global_load_dword v88, v[26:27], off nt
	s_nop 0
	v_addc_co_u32_e32 v25, vcc, 0, v1, vcc
	global_load_dword v6, v[24:25], off offset:2048 nt
	s_mov_b32 s13, 0x14000
	v_add_co_u32_e32 v22, vcc, s13, v0
	s_mov_b32 s13, 0x16000
	s_nop 0
	v_addc_co_u32_e32 v23, vcc, 0, v1, vcc
	v_add_co_u32_e32 v20, vcc, s13, v0
	s_mov_b32 s13, 0x18000
	s_nop 0
	v_addc_co_u32_e32 v21, vcc, 0, v1, vcc
	v_add_co_u32_e32 v16, vcc, s13, v0
	global_load_dword v58, v[22:23], off nt
	global_load_dword v96, v[20:21], off offset:2048 nt
	v_addc_co_u32_e32 v17, vcc, 0, v1, vcc
	global_load_dword v7, v[16:17], off nt
	global_load_dword v59, v[16:17], off offset:2048 nt
	s_mov_b32 s13, 0x1b000
	v_add_co_u32_e32 v18, vcc, s13, v0
	s_mov_b32 s13, 0x1c000
	s_nop 0
	v_addc_co_u32_e32 v19, vcc, 0, v1, vcc
	v_add_co_u32_e32 v14, vcc, s13, v0
	global_load_dword v100, v[18:19], off nt
	s_nop 0
	v_addc_co_u32_e32 v15, vcc, 0, v1, vcc
	global_load_dword v62, v[14:15], off offset:2048 nt
	s_waitcnt vmcnt(18)
	v_lshlrev_b32_e32 v54, 16, v2
	v_and_b32_e32 v2, 0xffff0000, v2
	v_mul_f32_e32 v2, 0xbfb8aa3b, v2
	v_exp_f32_e32 v2, v2
	s_mov_b32 s13, 0x1d000
	v_add_co_u32_e32 v12, vcc, s13, v0
	v_add_f32_e32 v2, 1.0, v2
	v_rcp_f32_e32 v55, v2
	s_waitcnt vmcnt(15)
	v_lshlrev_b32_e32 v2, 16, v3
	v_mul_f32_e32 v2, 0xbfb8aa3b, v2
	v_exp_f32_e32 v2, v2
	v_addc_co_u32_e32 v13, vcc, 0, v1, vcc
	global_load_dword v63, v[12:13], off nt
	v_add_f32_e32 v2, 1.0, v2
	v_rcp_f32_e32 v60, v2
	v_and_b32_e32 v2, 0xffff0000, v3
	v_mul_f32_e32 v2, 0xbfb8aa3b, v2
	v_exp_f32_e32 v2, v2
	s_mov_b32 s13, 0x1f000
	v_add_co_u32_e32 v10, vcc, s13, v0
	v_add_f32_e32 v2, 1.0, v2
	v_rcp_f32_e32 v61, v2
	s_waitcnt vmcnt(13)
	v_lshlrev_b32_e32 v2, 16, v4
	v_mul_f32_e32 v2, 0xbfb8aa3b, v2
	v_exp_f32_e32 v2, v2
	v_addc_co_u32_e32 v11, vcc, 0, v1, vcc
	global_load_dword v47, v[10:11], off offset:2048 nt
	v_add_f32_e32 v2, 1.0, v2
	v_rcp_f32_e32 v68, v2
	v_and_b32_e32 v2, 0xffff0000, v4
	v_mul_f32_e32 v2, 0xbfb8aa3b, v2
	v_exp_f32_e32 v2, v2
	s_mov_b32 s13, 0x21000
	v_add_co_u32_e32 v8, vcc, s13, v0
	v_add_f32_e32 v2, 1.0, v2
	v_rcp_f32_e32 v69, v2
	s_waitcnt vmcnt(11)
	v_lshlrev_b32_e32 v2, 16, v5
	v_mul_f32_e32 v2, 0xbfb8aa3b, v2
	v_exp_f32_e32 v2, v2
	v_readlane_b32 s13, v251, 45
	v_addc_co_u32_e32 v9, vcc, 0, v1, vcc
	v_add_f32_e32 v2, 1.0, v2
	v_rcp_f32_e32 v76, v2
	v_and_b32_e32 v2, 0xffff0000, v5
	v_mul_f32_e32 v2, 0xbfb8aa3b, v2
	v_exp_f32_e32 v2, v2
	v_mul_f32_e32 v54, 0xbfb8aa3b, v54
	v_exp_f32_e32 v54, v54
	global_load_dword v0, v[8:9], off nt
	global_load_dword v1, v[8:9], off offset:2048 nt
	v_lshrrev_b32_e32 v248, 3, v220
	v_mul_u32_u24_e32 v248, 0x4800, v248
	v_bfe_u32 v249, v220, 1, 2
	v_min_u32_e32 v249, 2, v249
	v_lshrrev_b32_e32 v252, 1, v249
	v_mul_u32_u24_e32 v249, 0x1800, v249
	v_lshlrev_b32_e32 v252, 12, v252
	v_sub_u32_e32 v249, v249, v252
	v_and_b32_e32 v252, 1, v220
	v_lshlrev_b32_e32 v252, 7, v252
	v_add3_u32 v248, v248, v249, v252
	s_cmpk_lt_i32 s89, 0x300
	s_cselect_b32 s32, 0x2400000, 0
	v_add_u32_e32 v248, s32, v248
	global_load_dword v248, v248, s[58:59]
	v_add_f32_e32 v2, 1.0, v2
	v_rcp_f32_e32 v77, v2
	s_waitcnt vmcnt(11)
	v_lshlrev_b32_e32 v2, 16, v6
	v_mul_f32_e32 v2, 0xbfb8aa3b, v2
	v_exp_f32_e32 v2, v2
	v_add_f32_e32 v54, 1.0, v54
	v_rcp_f32_e32 v54, v54
	v_add_f32_e32 v2, 1.0, v2
	v_rcp_f32_e32 v84, v2
	v_and_b32_e32 v2, 0xffff0000, v6
	v_mul_f32_e32 v2, 0xbfb8aa3b, v2
	v_exp_f32_e32 v2, v2
	s_waitcnt vmcnt(4)
	v_lshlrev_b32_e32 v6, 16, v63
	v_add_f32_e32 v2, 1.0, v2
	v_rcp_f32_e32 v85, v2
	v_lshlrev_b32_e32 v2, 16, v7
	v_mul_f32_e32 v2, 0xbfb8aa3b, v2
	v_exp_f32_e32 v2, v2
	v_mul_f32_e32 v6, 0xbfb8aa3b, v6
	v_exp_f32_e32 v6, v6
	v_add_f32_e32 v2, 1.0, v2
	v_rcp_f32_e32 v92, v2
	v_and_b32_e32 v2, 0xffff0000, v7
	v_mul_f32_e32 v2, 0xbfb8aa3b, v2
	v_exp_f32_e32 v2, v2
	v_and_b32_e32 v7, 0xffff0000, v63
	v_mul_f32_e32 v7, 0xbfb8aa3b, v7
	v_exp_f32_e32 v7, v7
	v_add_f32_e32 v2, 1.0, v2
	v_rcp_f32_e32 v93, v2
	v_lshlrev_b32_e32 v2, 16, v62
	v_mul_f32_e32 v2, 0xbfb8aa3b, v2
	v_exp_f32_e32 v2, v2
	v_add_f32_e32 v6, 1.0, v6
	v_add_f32_e32 v7, 1.0, v7
	v_rcp_f32_e32 v6, v6
	v_add_f32_e32 v2, 1.0, v2
	v_rcp_f32_e32 v4, v2
	v_and_b32_e32 v2, 0xffff0000, v62
	v_lshlrev_b32_e32 v62, 16, v59
	v_and_b32_e32 v59, 0xffff0000, v59
	v_mul_f32_e32 v59, 0xbfb8aa3b, v59
	v_exp_f32_e32 v59, v59
	v_mul_f32_e32 v62, 0xbfb8aa3b, v62
	v_exp_f32_e32 v62, v62
	v_mul_f32_e32 v2, 0xbfb8aa3b, v2
	v_add_f32_e32 v59, 1.0, v59
	v_rcp_f32_e32 v95, v59
	v_lshlrev_b32_e32 v59, 16, v58
	v_and_b32_e32 v58, 0xffff0000, v58
	v_mul_f32_e32 v58, 0xbfb8aa3b, v58
	v_exp_f32_e32 v58, v58
	v_mul_f32_e32 v59, 0xbfb8aa3b, v59
	v_exp_f32_e32 v59, v59
	v_add_f32_e32 v62, 1.0, v62
	v_add_f32_e32 v58, 1.0, v58
	v_rcp_f32_e32 v87, v58
	v_lshlrev_b32_e32 v58, 16, v51
	v_and_b32_e32 v51, 0xffff0000, v51
	v_mul_f32_e32 v51, 0xbfb8aa3b, v51
	v_exp_f32_e32 v51, v51
	v_mul_f32_e32 v58, 0xbfb8aa3b, v58
	v_exp_f32_e32 v58, v58
	v_add_f32_e32 v59, 1.0, v59
	v_add_f32_e32 v51, 1.0, v51
	v_rcp_f32_e32 v79, v51
	v_lshlrev_b32_e32 v51, 16, v49
	v_and_b32_e32 v49, 0xffff0000, v49
	v_mul_f32_e32 v49, 0xbfb8aa3b, v49
	v_exp_f32_e32 v49, v49
	v_mul_f32_e32 v51, 0xbfb8aa3b, v51
	v_exp_f32_e32 v51, v51
	v_rcp_f32_e32 v86, v59
	v_add_f32_e32 v49, 1.0, v49
	v_rcp_f32_e32 v71, v49
	v_lshlrev_b32_e32 v49, 16, v48
	v_and_b32_e32 v48, 0xffff0000, v48
	v_mul_f32_e32 v48, 0xbfb8aa3b, v48
	v_exp_f32_e32 v48, v48
	v_add_f32_e32 v51, 1.0, v51
	v_rcp_f32_e32 v70, v51
	v_mul_f32_e32 v51, 0xbfb8aa3b, v67
	v_add_f32_e32 v48, 1.0, v48
	v_rcp_f32_e32 v63, v48
	v_lshlrev_b32_e32 v48, 16, v46
	v_and_b32_e32 v46, 0xffff0000, v46
	v_mul_f32_e32 v46, 0xbfb8aa3b, v46
	v_mul_f32_e32 v48, 0xbfb8aa3b, v48
	v_exp_f32_e32 v46, v46
	v_exp_f32_e32 v48, v48
	v_exp_f32_e32 v51, v51
	v_add_f32_e32 v58, 1.0, v58
	v_add_f32_e32 v46, 1.0, v46
	v_add_f32_e32 v48, 1.0, v48
	v_rcp_f32_e32 v59, v46
	v_lshlrev_b32_e32 v46, 2, v132
	v_add_f32_e32 v51, 1.0, v51
	v_rcp_f32_e32 v78, v58
	v_rcp_f32_e32 v58, v48
	v_lshl_or_b32 v48, s14, 9, v46
	s_lshl_b64 s[14:15], s[54:55], 11
	v_rcp_f32_e32 v51, v51
	s_add_u32 s13, s13, s14
	v_readlane_b32 s14, v251, 46
	s_addc_u32 s14, s14, s15
	s_add_u32 s60, s13, s12
	v_div_scale_f32 v65, s[12:13], v53, v53, 1.0
	v_pk_mul_f32 v[50:51], v[50:51], v[66:67]
	v_rcp_f32_e32 v66, v65
	v_mul_f32_e32 v49, 0xbfb8aa3b, v49
	v_exp_f32_e32 v49, v49
	v_rcp_f32_e32 v94, v62
	v_fma_f32 v67, -v65, v66, 1.0
	v_fmac_f32_e32 v66, v67, v66
	v_div_scale_f32 v67, vcc, 1.0, v53, 1.0
	v_mul_f32_e32 v73, v67, v66
	v_fma_f32 v74, -v65, v73, v67
	v_fmac_f32_e32 v73, v74, v66
	v_fma_f32 v65, -v65, v73, v67
	v_div_fmas_f32 v65, v65, v66, v73
	v_div_fixup_f32 v109, v65, v53, 1.0
	v_div_scale_f32 v53, s[12:13], v52, v52, 1.0
	v_rcp_f32_e32 v65, v53
	v_add_f32_e32 v49, 1.0, v49
	v_rcp_f32_e32 v62, v49
	v_exp_f32_e32 v2, v2
	v_fma_f32 v66, -v53, v65, 1.0
	v_fmac_f32_e32 v65, v66, v65
	v_div_scale_f32 v66, vcc, 1.0, v52, 1.0
	v_mul_f32_e32 v67, v66, v65
	v_fma_f32 v73, -v53, v67, v66
	v_fmac_f32_e32 v67, v73, v65
	v_fma_f32 v53, -v53, v67, v66
	v_div_fmas_f32 v53, v53, v65, v67
	v_div_fixup_f32 v108, v53, v52, 1.0
	v_pk_add_f32 v[110:111], v[108:109], 1.0 op_sel_hi:[1,0] neg_lo:[1,0] neg_hi:[1,0]
	v_add_f32_e32 v2, 1.0, v2
	v_pk_fma_f32 v[52:53], v[110:111], v[54:55], v[108:109]
	v_pk_fma_f32 v[60:61], v[110:111], v[60:61], v[108:109]
	v_cmp_gt_f32_e32 vcc, s20, v52
	v_pk_fma_f32 v[68:69], v[110:111], v[68:69], v[108:109]
	v_pk_fma_f32 v[76:77], v[110:111], v[76:77], v[108:109]
	v_cndmask_b32_e64 v54, 0, 32, vcc
	v_ldexp_f32 v54, v52, v54
	v_log_f32_e32 v54, v54
	v_pk_fma_f32 v[84:85], v[110:111], v[84:85], v[108:109]
	v_pk_fma_f32 v[92:93], v[110:111], v[92:93], v[108:109]
	v_rcp_f32_e32 v5, v2
	v_mul_f32_e32 v55, 0x3f317217, v54
	v_fma_f32 v55, v54, s21, -v55
	v_fmac_f32_e32 v55, 0x3377d1cf, v54
	v_fmac_f32_e32 v55, 0x3f317217, v54
	v_cmp_lt_f32_e64 s[54:55], |v54|, s10
	v_pk_fma_f32 v[4:5], v[110:111], v[4:5], v[108:109]
	v_rcp_f32_e32 v7, v7
	v_cndmask_b32_e64 v54, v54, v55, s[54:55]
	v_cndmask_b32_e32 v55, 0, v223, vcc
	v_cmp_gt_f32_e32 vcc, s20, v53
	v_sub_f32_e32 v54, v54, v55
	s_waitcnt vmcnt(2)
	v_lshlrev_b32_e32 v2, 16, v0
	v_cndmask_b32_e64 v55, 0, 32, vcc
	v_ldexp_f32 v55, v53, v55
	v_log_f32_e32 v55, v55
	v_and_b32_e32 v0, 0xffff0000, v0
	v_mul_f32_e32 v2, 0xbfb8aa3b, v2
	v_mul_f32_e32 v0, 0xbfb8aa3b, v0
	v_mul_f32_e32 v65, 0x3f317217, v55
	v_fma_f32 v65, v55, s21, -v65
	v_fmac_f32_e32 v65, 0x3377d1cf, v55
	v_fmac_f32_e32 v65, 0x3f317217, v55
	v_cmp_lt_f32_e64 s[54:55], |v55|, s10
	v_exp_f32_e32 v2, v2
	v_exp_f32_e32 v0, v0
	v_cndmask_b32_e64 v55, v55, v65, s[54:55]
	v_cndmask_b32_e32 v65, 0, v223, vcc
	v_sub_f32_e32 v55, v55, v65
	v_div_scale_f32 v65, s[12:13], v57, v57, 1.0
	v_rcp_f32_e32 v66, v65
	v_pk_add_f32 v[54:55], v[54:55], 0 op_sel_hi:[1,0]
	v_add_f32_e32 v2, 1.0, v2
	v_add_f32_e32 v0, 1.0, v0
	v_fma_f32 v67, -v65, v66, 1.0
	v_fmac_f32_e32 v66, v67, v66
	v_div_scale_f32 v67, vcc, 1.0, v57, 1.0
	v_mul_f32_e32 v73, v67, v66
	v_fma_f32 v74, -v65, v73, v67
	v_fmac_f32_e32 v73, v74, v66
	v_fma_f32 v65, -v65, v73, v67
	v_div_fmas_f32 v65, v65, v66, v73
	v_div_fixup_f32 v113, v65, v57, 1.0
	v_div_scale_f32 v57, s[12:13], v56, v56, 1.0
	v_rcp_f32_e32 v65, v57
	v_rcp_f32_e32 v2, v2
	v_rcp_f32_e32 v3, v0
	s_waitcnt vmcnt(1)
	v_lshlrev_b32_e32 v0, 16, v1
	v_fma_f32 v66, -v57, v65, 1.0
	v_fmac_f32_e32 v65, v66, v65
	v_div_scale_f32 v66, vcc, 1.0, v56, 1.0
	v_mul_f32_e32 v67, v66, v65
	v_fma_f32 v73, -v57, v67, v66
	v_fmac_f32_e32 v67, v73, v65
	v_fma_f32 v57, -v57, v67, v66
	v_div_fmas_f32 v57, v57, v65, v67
	v_div_fixup_f32 v112, v57, v56, 1.0
	v_pk_add_f32 v[116:117], v[112:113], 1.0 op_sel_hi:[1,0] neg_lo:[1,0] neg_hi:[1,0]
	v_pk_fma_f32 v[2:3], v[110:111], v[2:3], v[108:109]
	v_pk_fma_f32 v[56:57], v[116:117], v[58:59], v[112:113]
	v_pk_fma_f32 v[62:63], v[116:117], v[62:63], v[112:113]
	v_cmp_gt_f32_e32 vcc, s20, v56
	v_pk_fma_f32 v[70:71], v[116:117], v[70:71], v[112:113]
	v_pk_fma_f32 v[78:79], v[116:117], v[78:79], v[112:113]
	v_cndmask_b32_e64 v58, 0, 32, vcc
	v_ldexp_f32 v58, v56, v58
	v_log_f32_e32 v58, v58
	v_pk_fma_f32 v[86:87], v[116:117], v[86:87], v[112:113]
	v_pk_fma_f32 v[94:95], v[116:117], v[94:95], v[112:113]
	v_pk_fma_f32 v[6:7], v[116:117], v[6:7], v[112:113]
	v_mul_f32_e32 v59, 0x3f317217, v58
	v_fma_f32 v59, v58, s21, -v59
	v_fmac_f32_e32 v59, 0x3377d1cf, v58
	v_fmac_f32_e32 v59, 0x3f317217, v58
	v_cmp_lt_f32_e64 s[54:55], |v58|, s10
	v_pk_add_f32 v[104:105], v[6:7], 1.0 op_sel_hi:[1,0] neg_lo:[1,0] neg_hi:[1,0]
	v_and_b32_e32 v1, 0xffff0000, v1
	v_cndmask_b32_e64 v58, v58, v59, s[54:55]
	v_cndmask_b32_e32 v59, 0, v223, vcc
	v_cmp_gt_f32_e32 vcc, s20, v57
	v_sub_f32_e32 v114, v58, v59
	v_mul_f32_e32 v0, 0xbfb8aa3b, v0
	v_cndmask_b32_e64 v58, 0, 32, vcc
	v_ldexp_f32 v58, v57, v58
	v_log_f32_e32 v58, v58
	v_mul_f32_e32 v1, 0xbfb8aa3b, v1
	v_exp_f32_e32 v0, v0
	v_exp_f32_e32 v1, v1
	v_mul_f32_e32 v59, 0x3f317217, v58
	v_fma_f32 v59, v58, s21, -v59
	v_fmac_f32_e32 v59, 0x3377d1cf, v58
	v_fmac_f32_e32 v59, 0x3f317217, v58
	v_cmp_lt_f32_e64 s[54:55], |v58|, s10
	v_add_f32_e32 v0, 1.0, v0
	v_add_f32_e32 v1, 1.0, v1
	v_cndmask_b32_e64 v58, v58, v59, s[54:55]
	v_cndmask_b32_e32 v59, 0, v223, vcc
	v_sub_f32_e32 v115, v58, v59
	v_pk_add_f32 v[58:59], v[56:57], 1.0 op_sel_hi:[1,0] neg_lo:[1,0] neg_hi:[1,0]
	v_lshlrev_b32_e32 v56, 16, v64
	v_and_b32_e32 v57, 0xffff0000, v64
	v_mul_f32_e32 v64, 0xbfb8aa3b, v56
	v_mul_f32_e32 v65, 0xbfb8aa3b, v57
	v_exp_f32_e32 v64, v64
	v_exp_f32_e32 v65, v65
	v_cmp_gt_f32_e32 vcc, s20, v60
	v_rcp_f32_e32 v0, v0
	v_add_f32_e32 v64, 1.0, v64
	v_add_f32_e32 v65, 1.0, v65
	v_rcp_f32_e32 v64, v64
	v_rcp_f32_e32 v65, v65
	v_rcp_f32_e32 v1, v1
	v_pk_add_f32 v[108:109], v[2:3], 1.0 op_sel_hi:[1,0] neg_lo:[1,0] neg_hi:[1,0]
	v_add_u32_e32 v141, 0, v48
	v_pk_mul_f32 v[56:57], v[64:65], v[56:57]
	v_cndmask_b32_e64 v64, 0, 32, vcc
	v_ldexp_f32 v64, v60, v64
	v_log_f32_e32 v64, v64
	v_pk_fma_f32 v[0:1], v[116:117], v[0:1], v[112:113]
	v_mov_b32_e32 v154, v55
	v_pk_add_f32 v[112:113], v[0:1], 1.0 op_sel_hi:[1,0] neg_lo:[1,0] neg_hi:[1,0]
	v_mul_f32_e32 v65, 0x3f317217, v64
	v_fma_f32 v65, v64, s21, -v65
	v_fmac_f32_e32 v65, 0x3377d1cf, v64
	v_fmac_f32_e32 v65, 0x3f317217, v64
	v_cmp_lt_f32_e64 s[54:55], |v64|, s10
	v_pk_mul_f32 v[50:51], v[50:51], s[6:7] op_sel_hi:[1,0]
	v_pk_add_f32 v[52:53], v[52:53], 1.0 op_sel_hi:[1,0] neg_lo:[1,0] neg_hi:[1,0]
	v_cndmask_b32_e64 v64, v64, v65, s[54:55]
	v_cndmask_b32_e32 v65, 0, v223, vcc
	v_cmp_gt_f32_e32 vcc, s20, v61
	v_sub_f32_e32 v64, v64, v65
	v_pk_mul_f32 v[56:57], v[56:57], s[6:7] op_sel_hi:[1,0]
	v_cndmask_b32_e64 v65, 0, 32, vcc
	v_ldexp_f32 v65, v61, v65
	v_log_f32_e32 v65, v65
	s_addc_u32 s61, s14, 0
	v_pk_add_f32 v[60:61], v[60:61], 1.0 op_sel_hi:[1,0] neg_lo:[1,0] neg_hi:[1,0]
	v_lshl_add_u64 v[48:49], s[60:61], 0, v[128:129]
	v_mul_f32_e32 v66, 0x3f317217, v65
	v_fma_f32 v66, v65, s21, -v66
	v_fmac_f32_e32 v66, 0x3377d1cf, v65
	v_fmac_f32_e32 v66, 0x3f317217, v65
	v_cmp_lt_f32_e64 s[54:55], |v65|, s10
	s_cmp_gt_u32 s9, 63
	s_nop 0
	v_cndmask_b32_e64 v65, v65, v66, s[54:55]
	v_cndmask_b32_e32 v66, 0, v223, vcc
	v_cmp_gt_f32_e32 vcc, s20, v62
	v_sub_f32_e32 v65, v65, v66
	v_pk_add_f32 v[64:65], v[54:55], v[64:65]
	v_cndmask_b32_e64 v66, 0, 32, vcc
	v_ldexp_f32 v66, v62, v66
	v_log_f32_e32 v66, v66
	s_nop 0
	v_mul_f32_e32 v67, 0x3f317217, v66
	v_fma_f32 v67, v66, s21, -v67
	v_fmac_f32_e32 v67, 0x3377d1cf, v66
	v_fmac_f32_e32 v67, 0x3f317217, v66
	v_cmp_lt_f32_e64 s[54:55], |v66|, s10
	s_nop 1
	v_cndmask_b32_e64 v66, v66, v67, s[54:55]
	v_cndmask_b32_e32 v67, 0, v223, vcc
	v_cmp_gt_f32_e32 vcc, s20, v63
	v_sub_f32_e32 v122, v66, v67
	s_nop 0
	v_cndmask_b32_e64 v66, 0, 32, vcc
	v_ldexp_f32 v66, v63, v66
	v_log_f32_e32 v66, v66
	s_nop 0
	v_mul_f32_e32 v67, 0x3f317217, v66
	v_fma_f32 v67, v66, s21, -v67
	v_fmac_f32_e32 v67, 0x3377d1cf, v66
	v_fmac_f32_e32 v67, 0x3f317217, v66
	v_cmp_lt_f32_e64 s[54:55], |v66|, s10
	s_nop 1
	v_cndmask_b32_e64 v66, v66, v67, s[54:55]
	v_cndmask_b32_e32 v67, 0, v223, vcc
	v_sub_f32_e32 v123, v66, v67
	v_pk_add_f32 v[66:67], v[62:63], 1.0 op_sel_hi:[1,0] neg_lo:[1,0] neg_hi:[1,0]
	v_lshlrev_b32_e32 v62, 16, v72
	v_and_b32_e32 v63, 0xffff0000, v72
	v_mul_f32_e32 v72, 0xbfb8aa3b, v62
	v_mul_f32_e32 v73, 0xbfb8aa3b, v63
	v_exp_f32_e32 v72, v72
	v_exp_f32_e32 v73, v73
	v_cmp_gt_f32_e32 vcc, s20, v68
	v_add_f32_e32 v72, 1.0, v72
	v_add_f32_e32 v73, 1.0, v73
	v_rcp_f32_e32 v72, v72
	v_rcp_f32_e32 v73, v73
	s_nop 0
	v_pk_mul_f32 v[62:63], v[72:73], v[62:63]
	v_cndmask_b32_e64 v72, 0, 32, vcc
	v_ldexp_f32 v72, v68, v72
	v_log_f32_e32 v72, v72
	v_pk_mul_f32 v[62:63], v[62:63], s[6:7] op_sel_hi:[1,0]
	v_mul_f32_e32 v73, 0x3f317217, v72
	v_fma_f32 v73, v72, s21, -v73
	v_fmac_f32_e32 v73, 0x3377d1cf, v72
	v_fmac_f32_e32 v73, 0x3f317217, v72
	v_cmp_lt_f32_e64 s[54:55], |v72|, s10
	s_nop 1
	v_cndmask_b32_e64 v72, v72, v73, s[54:55]
	v_cndmask_b32_e32 v73, 0, v223, vcc
	v_cmp_gt_f32_e32 vcc, s20, v69
	v_sub_f32_e32 v72, v72, v73
	s_nop 0
	v_cndmask_b32_e64 v73, 0, 32, vcc
	v_ldexp_f32 v73, v69, v73
	v_log_f32_e32 v73, v73
	v_pk_add_f32 v[68:69], v[68:69], 1.0 op_sel_hi:[1,0] neg_lo:[1,0] neg_hi:[1,0]
	v_mul_f32_e32 v74, 0x3f317217, v73
	v_fma_f32 v74, v73, s21, -v74
	v_fmac_f32_e32 v74, 0x3377d1cf, v73
	v_fmac_f32_e32 v74, 0x3f317217, v73
	v_cmp_lt_f32_e64 s[54:55], |v73|, s10
	s_nop 1
	v_cndmask_b32_e64 v73, v73, v74, s[54:55]
	v_cndmask_b32_e32 v74, 0, v223, vcc
	v_sub_f32_e32 v73, v73, v74
	v_cmp_gt_f32_e32 vcc, s20, v70
	v_pk_add_f32 v[74:75], v[64:65], v[72:73]
	s_nop 0
	v_cndmask_b32_e64 v72, 0, 32, vcc
	v_ldexp_f32 v72, v70, v72
	v_log_f32_e32 v72, v72
	s_nop 0
	v_mul_f32_e32 v73, 0x3f317217, v72
	v_fma_f32 v73, v72, s21, -v73
	v_fmac_f32_e32 v73, 0x3377d1cf, v72
	v_fmac_f32_e32 v73, 0x3f317217, v72
	v_cmp_lt_f32_e64 s[54:55], |v72|, s10
	s_nop 1
	v_cndmask_b32_e64 v72, v72, v73, s[54:55]
	v_cndmask_b32_e32 v73, 0, v223, vcc
	v_cmp_gt_f32_e32 vcc, s20, v71
	v_sub_f32_e32 v142, v72, v73
	s_nop 0
	v_cndmask_b32_e64 v72, 0, 32, vcc
	v_ldexp_f32 v72, v71, v72
	v_log_f32_e32 v72, v72
	s_nop 0
	v_mul_f32_e32 v73, 0x3f317217, v72
	v_fma_f32 v73, v72, s21, -v73
	v_fmac_f32_e32 v73, 0x3377d1cf, v72
	v_fmac_f32_e32 v73, 0x3f317217, v72
	v_cmp_lt_f32_e64 s[54:55], |v72|, s10
	s_nop 1
	v_cndmask_b32_e64 v72, v72, v73, s[54:55]
	v_cndmask_b32_e32 v73, 0, v223, vcc
	v_sub_f32_e32 v143, v72, v73
	v_pk_add_f32 v[72:73], v[70:71], 1.0 op_sel_hi:[1,0] neg_lo:[1,0] neg_hi:[1,0]
	v_lshlrev_b32_e32 v70, 16, v80
	v_and_b32_e32 v71, 0xffff0000, v80
	v_mul_f32_e32 v80, 0xbfb8aa3b, v70
	v_mul_f32_e32 v81, 0xbfb8aa3b, v71
	v_exp_f32_e32 v80, v80
	v_exp_f32_e32 v81, v81
	v_cmp_gt_f32_e32 vcc, s20, v76
	v_add_f32_e32 v80, 1.0, v80
	v_add_f32_e32 v81, 1.0, v81
	v_rcp_f32_e32 v80, v80
	v_rcp_f32_e32 v81, v81
	s_nop 0
	v_pk_mul_f32 v[70:71], v[80:81], v[70:71]
	v_cndmask_b32_e64 v80, 0, 32, vcc
	v_ldexp_f32 v80, v76, v80
	v_log_f32_e32 v80, v80
	v_pk_mul_f32 v[70:71], v[70:71], s[6:7] op_sel_hi:[1,0]
	v_mul_f32_e32 v81, 0x3f317217, v80
	v_fma_f32 v81, v80, s21, -v81
	v_fmac_f32_e32 v81, 0x3377d1cf, v80
	v_fmac_f32_e32 v81, 0x3f317217, v80
	v_cmp_lt_f32_e64 s[54:55], |v80|, s10
	s_nop 1
	v_cndmask_b32_e64 v80, v80, v81, s[54:55]
	v_cndmask_b32_e32 v81, 0, v223, vcc
	v_cmp_gt_f32_e32 vcc, s20, v77
	v_sub_f32_e32 v80, v80, v81
	s_nop 0
	v_cndmask_b32_e64 v81, 0, 32, vcc
	v_ldexp_f32 v81, v77, v81
	v_log_f32_e32 v81, v81
	v_pk_add_f32 v[76:77], v[76:77], 1.0 op_sel_hi:[1,0] neg_lo:[1,0] neg_hi:[1,0]
	v_mul_f32_e32 v82, 0x3f317217, v81
	v_fma_f32 v82, v81, s21, -v82
	v_fmac_f32_e32 v82, 0x3377d1cf, v81
	v_fmac_f32_e32 v82, 0x3f317217, v81
	v_cmp_lt_f32_e64 s[54:55], |v81|, s10
	s_nop 1
	v_cndmask_b32_e64 v81, v81, v82, s[54:55]
	v_cndmask_b32_e32 v82, 0, v223, vcc
	v_cmp_gt_f32_e32 vcc, s20, v78
	v_sub_f32_e32 v81, v81, v82
	v_pk_add_f32 v[80:81], v[74:75], v[80:81]
	v_cndmask_b32_e64 v82, 0, 32, vcc
	v_ldexp_f32 v82, v78, v82
	v_log_f32_e32 v82, v82
	s_nop 0
	v_mul_f32_e32 v83, 0x3f317217, v82
	v_fma_f32 v83, v82, s21, -v83
	v_fmac_f32_e32 v83, 0x3377d1cf, v82
	v_fmac_f32_e32 v83, 0x3f317217, v82
	v_cmp_lt_f32_e64 s[54:55], |v82|, s10
	s_nop 1
	v_cndmask_b32_e64 v82, v82, v83, s[54:55]
	v_cndmask_b32_e32 v83, 0, v223, vcc
	v_cmp_gt_f32_e32 vcc, s20, v79
	v_sub_f32_e32 v126, v82, v83
	s_nop 0
	v_cndmask_b32_e64 v82, 0, 32, vcc
	v_ldexp_f32 v82, v79, v82
	v_log_f32_e32 v82, v82
	s_nop 0
	v_mul_f32_e32 v83, 0x3f317217, v82
	v_fma_f32 v83, v82, s21, -v83
	v_fmac_f32_e32 v83, 0x3377d1cf, v82
	v_fmac_f32_e32 v83, 0x3f317217, v82
	v_cmp_lt_f32_e64 s[54:55], |v82|, s10
	s_nop 1
	v_cndmask_b32_e64 v82, v82, v83, s[54:55]
	v_cndmask_b32_e32 v83, 0, v223, vcc
	v_sub_f32_e32 v127, v82, v83
	v_pk_add_f32 v[82:83], v[78:79], 1.0 op_sel_hi:[1,0] neg_lo:[1,0] neg_hi:[1,0]
	v_lshlrev_b32_e32 v78, 16, v88
	v_and_b32_e32 v79, 0xffff0000, v88
	v_mul_f32_e32 v88, 0xbfb8aa3b, v78
	v_mul_f32_e32 v89, 0xbfb8aa3b, v79
	v_exp_f32_e32 v88, v88
	v_exp_f32_e32 v89, v89
	v_cmp_gt_f32_e32 vcc, s20, v84
	v_add_f32_e32 v88, 1.0, v88
	v_add_f32_e32 v89, 1.0, v89
	v_rcp_f32_e32 v88, v88
	v_rcp_f32_e32 v89, v89
	s_nop 0
	v_pk_mul_f32 v[78:79], v[88:89], v[78:79]
	v_cndmask_b32_e64 v88, 0, 32, vcc
	v_ldexp_f32 v88, v84, v88
	v_log_f32_e32 v88, v88
	v_pk_mul_f32 v[78:79], v[78:79], s[6:7] op_sel_hi:[1,0]
	v_mul_f32_e32 v89, 0x3f317217, v88
	v_fma_f32 v89, v88, s21, -v89
	v_fmac_f32_e32 v89, 0x3377d1cf, v88
	v_fmac_f32_e32 v89, 0x3f317217, v88
	v_cmp_lt_f32_e64 s[54:55], |v88|, s10
	s_nop 1
	v_cndmask_b32_e64 v88, v88, v89, s[54:55]
	v_cndmask_b32_e32 v89, 0, v223, vcc
	v_cmp_gt_f32_e32 vcc, s20, v85
	v_sub_f32_e32 v88, v88, v89
	s_nop 0
	v_cndmask_b32_e64 v89, 0, 32, vcc
	v_ldexp_f32 v89, v85, v89
	v_log_f32_e32 v89, v89
	v_pk_add_f32 v[84:85], v[84:85], 1.0 op_sel_hi:[1,0] neg_lo:[1,0] neg_hi:[1,0]
	v_mul_f32_e32 v90, 0x3f317217, v89
	v_fma_f32 v90, v89, s21, -v90
	v_fmac_f32_e32 v90, 0x3377d1cf, v89
	v_fmac_f32_e32 v90, 0x3f317217, v89
	v_cmp_lt_f32_e64 s[54:55], |v89|, s10
	s_nop 1
	v_cndmask_b32_e64 v89, v89, v90, s[54:55]
	v_cndmask_b32_e32 v90, 0, v223, vcc
	v_cmp_gt_f32_e32 vcc, s20, v86
	v_sub_f32_e32 v89, v89, v90
	v_pk_add_f32 v[88:89], v[80:81], v[88:89]
	v_cndmask_b32_e64 v90, 0, 32, vcc
	v_ldexp_f32 v90, v86, v90
	v_log_f32_e32 v90, v90
	s_nop 0
	v_mul_f32_e32 v91, 0x3f317217, v90
	v_fma_f32 v91, v90, s21, -v91
	v_fmac_f32_e32 v91, 0x3377d1cf, v90
	v_fmac_f32_e32 v91, 0x3f317217, v90
	v_cmp_lt_f32_e64 s[54:55], |v90|, s10
	s_nop 1
	v_cndmask_b32_e64 v90, v90, v91, s[54:55]
	v_cndmask_b32_e32 v91, 0, v223, vcc
	v_cmp_gt_f32_e32 vcc, s20, v87
	v_sub_f32_e32 v124, v90, v91
	s_nop 0
	v_cndmask_b32_e64 v90, 0, 32, vcc
	v_ldexp_f32 v90, v87, v90
	v_log_f32_e32 v90, v90
	s_nop 0
	v_mul_f32_e32 v91, 0x3f317217, v90
	v_fma_f32 v91, v90, s21, -v91
	v_fmac_f32_e32 v91, 0x3377d1cf, v90
	v_fmac_f32_e32 v91, 0x3f317217, v90
	v_cmp_lt_f32_e64 s[54:55], |v90|, s10
	s_nop 1
	v_cndmask_b32_e64 v90, v90, v91, s[54:55]
	v_cndmask_b32_e32 v91, 0, v223, vcc
	v_sub_f32_e32 v125, v90, v91
	v_pk_add_f32 v[90:91], v[86:87], 1.0 op_sel_hi:[1,0] neg_lo:[1,0] neg_hi:[1,0]
	v_lshlrev_b32_e32 v86, 16, v96
	v_and_b32_e32 v87, 0xffff0000, v96
	v_mul_f32_e32 v96, 0xbfb8aa3b, v86
	v_mul_f32_e32 v97, 0xbfb8aa3b, v87
	v_exp_f32_e32 v96, v96
	v_exp_f32_e32 v97, v97
	v_cmp_gt_f32_e32 vcc, s20, v92
	v_add_f32_e32 v96, 1.0, v96
	v_add_f32_e32 v97, 1.0, v97
	v_rcp_f32_e32 v96, v96
	v_rcp_f32_e32 v97, v97
	s_nop 0
	v_pk_mul_f32 v[86:87], v[96:97], v[86:87]
	v_cndmask_b32_e64 v96, 0, 32, vcc
	v_ldexp_f32 v96, v92, v96
	v_log_f32_e32 v96, v96
	v_pk_mul_f32 v[86:87], v[86:87], s[6:7] op_sel_hi:[1,0]
	v_mul_f32_e32 v97, 0x3f317217, v96
	v_fma_f32 v97, v96, s21, -v97
	v_fmac_f32_e32 v97, 0x3377d1cf, v96
	v_fmac_f32_e32 v97, 0x3f317217, v96
	v_cmp_lt_f32_e64 s[54:55], |v96|, s10
	s_nop 1
	v_cndmask_b32_e64 v96, v96, v97, s[54:55]
	v_cndmask_b32_e32 v97, 0, v223, vcc
	v_cmp_gt_f32_e32 vcc, s20, v93
	v_sub_f32_e32 v96, v96, v97
	s_nop 0
	v_cndmask_b32_e64 v97, 0, 32, vcc
	v_ldexp_f32 v97, v93, v97
	v_log_f32_e32 v97, v97
	v_pk_add_f32 v[92:93], v[92:93], 1.0 op_sel_hi:[1,0] neg_lo:[1,0] neg_hi:[1,0]
	v_mul_f32_e32 v98, 0x3f317217, v97
	v_fma_f32 v98, v97, s21, -v98
	v_fmac_f32_e32 v98, 0x3377d1cf, v97
	v_fmac_f32_e32 v98, 0x3f317217, v97
	v_cmp_lt_f32_e64 s[54:55], |v97|, s10
	s_nop 1
	v_cndmask_b32_e64 v97, v97, v98, s[54:55]
	v_cndmask_b32_e32 v98, 0, v223, vcc
	v_cmp_gt_f32_e32 vcc, s20, v94
	v_sub_f32_e32 v97, v97, v98
	v_pk_add_f32 v[96:97], v[88:89], v[96:97]
	v_cndmask_b32_e64 v98, 0, 32, vcc
	v_ldexp_f32 v98, v94, v98
	v_log_f32_e32 v98, v98
	s_nop 0
	v_mul_f32_e32 v99, 0x3f317217, v98
	v_fma_f32 v99, v98, s21, -v99
	v_fmac_f32_e32 v99, 0x3377d1cf, v98
	v_fmac_f32_e32 v99, 0x3f317217, v98
	v_cmp_lt_f32_e64 s[54:55], |v98|, s10
	s_nop 1
	v_cndmask_b32_e64 v98, v98, v99, s[54:55]
	v_cndmask_b32_e32 v99, 0, v223, vcc
	v_cmp_gt_f32_e32 vcc, s20, v95
	v_sub_f32_e32 v120, v98, v99
	s_nop 0
	v_cndmask_b32_e64 v98, 0, 32, vcc
	v_ldexp_f32 v98, v95, v98
	v_log_f32_e32 v98, v98
	s_nop 0
	v_mul_f32_e32 v99, 0x3f317217, v98
	v_fma_f32 v99, v98, s21, -v99
	v_fmac_f32_e32 v99, 0x3377d1cf, v98
	v_fmac_f32_e32 v99, 0x3f317217, v98
	v_cmp_lt_f32_e64 s[54:55], |v98|, s10
	s_nop 1
	v_cndmask_b32_e64 v98, v98, v99, s[54:55]
	v_cndmask_b32_e32 v99, 0, v223, vcc
	v_sub_f32_e32 v121, v98, v99
	v_pk_add_f32 v[98:99], v[94:95], 1.0 op_sel_hi:[1,0] neg_lo:[1,0] neg_hi:[1,0]
	v_lshlrev_b32_e32 v94, 16, v100
	v_and_b32_e32 v95, 0xffff0000, v100
	v_mul_f32_e32 v100, 0xbfb8aa3b, v94
	v_mul_f32_e32 v101, 0xbfb8aa3b, v95
	v_exp_f32_e32 v100, v100
	v_exp_f32_e32 v101, v101
	v_cmp_gt_f32_e32 vcc, s20, v4
	v_add_f32_e32 v100, 1.0, v100
	v_add_f32_e32 v101, 1.0, v101
	v_rcp_f32_e32 v100, v100
	v_rcp_f32_e32 v101, v101
	s_nop 0
	v_pk_mul_f32 v[94:95], v[100:101], v[94:95]
	v_cndmask_b32_e64 v100, 0, 32, vcc
	v_ldexp_f32 v100, v4, v100
	v_log_f32_e32 v100, v100
	v_pk_mul_f32 v[94:95], v[94:95], s[6:7] op_sel_hi:[1,0]
	v_mul_f32_e32 v101, 0x3f317217, v100
	v_fma_f32 v101, v100, s21, -v101
	v_fmac_f32_e32 v101, 0x3377d1cf, v100
	v_fmac_f32_e32 v101, 0x3f317217, v100
	v_cmp_lt_f32_e64 s[54:55], |v100|, s10
	s_nop 1
	v_cndmask_b32_e64 v100, v100, v101, s[54:55]
	v_cndmask_b32_e32 v101, 0, v223, vcc
	v_cmp_gt_f32_e32 vcc, s20, v5
	v_sub_f32_e32 v102, v100, v101
	s_nop 0
	v_cndmask_b32_e64 v100, 0, 32, vcc
	v_ldexp_f32 v100, v5, v100
	v_log_f32_e32 v100, v100
	s_nop 0
	v_mul_f32_e32 v101, 0x3f317217, v100
	v_fma_f32 v101, v100, s21, -v101
	v_fmac_f32_e32 v101, 0x3377d1cf, v100
	v_fmac_f32_e32 v101, 0x3f317217, v100
	v_cmp_lt_f32_e64 s[54:55], |v100|, s10
	s_nop 1
	v_cndmask_b32_e64 v100, v100, v101, s[54:55]
	v_cndmask_b32_e32 v101, 0, v223, vcc
	v_cmp_gt_f32_e32 vcc, s20, v6
	v_sub_f32_e32 v103, v100, v101
	v_pk_add_f32 v[100:101], v[4:5], 1.0 op_sel_hi:[1,0] neg_lo:[1,0] neg_hi:[1,0]
	v_cndmask_b32_e64 v4, 0, 32, vcc
	v_ldexp_f32 v4, v6, v4
	v_log_f32_e32 v4, v4
	v_lshlrev_b32_e32 v6, 16, v47
	v_pk_add_f32 v[106:107], v[96:97], v[102:103]
	v_mul_f32_e32 v5, 0x3f317217, v4
	v_fma_f32 v5, v4, s21, -v5
	v_fmac_f32_e32 v5, 0x3377d1cf, v4
	v_fmac_f32_e32 v5, 0x3f317217, v4
	v_cmp_lt_f32_e64 s[54:55], |v4|, s10
	s_nop 1
	v_cndmask_b32_e64 v4, v4, v5, s[54:55]
	v_cndmask_b32_e32 v5, 0, v223, vcc
	v_cmp_gt_f32_e32 vcc, s20, v7
	v_sub_f32_e32 v4, v4, v5
	s_nop 0
	v_cndmask_b32_e64 v5, 0, 32, vcc
	v_ldexp_f32 v5, v7, v5
	v_log_f32_e32 v5, v5
	v_and_b32_e32 v7, 0xffff0000, v47
	v_mul_f32_e32 v47, 0xbfb8aa3b, v6
	v_exp_f32_e32 v47, v47
	v_mul_f32_e32 v102, 0x3f317217, v5
	v_fma_f32 v102, v5, s21, -v102
	v_fmac_f32_e32 v102, 0x3377d1cf, v5
	v_fmac_f32_e32 v102, 0x3f317217, v5
	v_cmp_lt_f32_e64 s[54:55], |v5|, s10
	v_add_f32_e32 v47, 1.0, v47
	s_nop 0
	v_cndmask_b32_e64 v5, v5, v102, s[54:55]
	v_cndmask_b32_e32 v102, 0, v223, vcc
	v_sub_f32_e32 v5, v5, v102
	v_rcp_f32_e32 v102, v47
	v_mul_f32_e32 v47, 0xbfb8aa3b, v7
	v_exp_f32_e32 v47, v47
	v_cmp_gt_f32_e32 vcc, s20, v2
	v_add_f32_e32 v47, 1.0, v47
	v_rcp_f32_e32 v103, v47
	s_nop 0
	v_pk_mul_f32 v[6:7], v[102:103], v[6:7]
	s_nop 0
	v_pk_mul_f32 v[102:103], v[6:7], s[6:7] op_sel_hi:[1,0]
	v_cndmask_b32_e64 v6, 0, 32, vcc
	v_ldexp_f32 v6, v2, v6
	v_log_f32_e32 v6, v6
	s_nop 0
	v_mul_f32_e32 v7, 0x3f317217, v6
	v_fma_f32 v7, v6, s21, -v7
	v_fmac_f32_e32 v7, 0x3377d1cf, v6
	v_fmac_f32_e32 v7, 0x3f317217, v6
	v_cmp_lt_f32_e64 s[54:55], |v6|, s10
	s_nop 1
	v_cndmask_b32_e64 v6, v6, v7, s[54:55]
	v_cndmask_b32_e32 v7, 0, v223, vcc
	v_cmp_gt_f32_e32 vcc, s20, v3
	v_sub_f32_e32 v6, v6, v7
	s_nop 0
	v_cndmask_b32_e64 v7, 0, 32, vcc
	v_ldexp_f32 v7, v3, v7
	v_log_f32_e32 v7, v7
	s_nop 0
	v_mul_f32_e32 v47, 0x3f317217, v7
	v_fma_f32 v47, v7, s21, -v47
	v_fmac_f32_e32 v47, 0x3377d1cf, v7
	v_fmac_f32_e32 v47, 0x3f317217, v7
	v_cmp_lt_f32_e64 s[54:55], |v7|, s10
	s_nop 1
	v_cndmask_b32_e64 v7, v7, v47, s[54:55]
	v_cndmask_b32_e32 v47, 0, v223, vcc
	v_cmp_gt_f32_e32 vcc, s20, v0
	v_sub_f32_e32 v7, v7, v47
	v_pk_add_f32 v[110:111], v[106:107], v[6:7]
	v_cndmask_b32_e64 v2, 0, 32, vcc
	v_ldexp_f32 v2, v0, v2
	v_log_f32_e32 v2, v2
	s_nop 0
	v_mul_f32_e32 v3, 0x3f317217, v2
	v_fma_f32 v3, v2, s21, -v3
	v_fmac_f32_e32 v3, 0x3377d1cf, v2
	v_fmac_f32_e32 v3, 0x3f317217, v2
	v_cmp_lt_f32_e64 s[54:55], |v2|, s10
	s_nop 1
	v_cndmask_b32_e64 v2, v2, v3, s[54:55]
	v_cndmask_b32_e32 v3, 0, v223, vcc
	v_cmp_gt_f32_e32 vcc, s20, v1
	v_sub_f32_e32 v2, v2, v3
	s_nop 0
	v_cndmask_b32_e64 v3, 0, 32, vcc
	v_ldexp_f32 v3, v1, v3
	v_log_f32_e32 v3, v3
	s_nop 0
	v_mul_f32_e32 v6, 0x3f317217, v3
	v_fma_f32 v6, v3, s21, -v6
	v_fmac_f32_e32 v6, 0x3377d1cf, v3
	v_fmac_f32_e32 v6, 0x3f317217, v3
	v_cmp_lt_f32_e64 s[54:55], |v3|, s10
	s_nop 1
	v_cndmask_b32_e64 v3, v3, v6, s[54:55]
	v_cndmask_b32_e32 v6, 0, v223, vcc
	v_sub_f32_e32 v3, v3, v6
	v_pk_add_f32 v[116:117], v[2:3], 0 op_sel_hi:[1,0]
	s_nop 0
	v_pk_add_f32 v[118:119], v[4:5], v[116:117]
	s_nop 0
	v_pk_add_f32 v[120:121], v[120:121], v[118:119]
	s_nop 0
	v_pk_add_f32 v[124:125], v[124:125], v[120:121]
	s_nop 0
	v_pk_add_f32 v[126:127], v[126:127], v[124:125]
	s_nop 0
	v_pk_add_f32 v[142:143], v[142:143], v[126:127]
	s_nop 0
	v_pk_add_f32 v[122:123], v[122:123], v[142:143]
	s_nop 0
	v_pk_add_f32 v[114:115], v[114:115], v[122:123]
	ds_write2st64_b64 v141, v[110:111], v[114:115] offset1:8
	s_waitcnt lgkmcnt(0)
	s_barrier
	ds_read2st64_b64 v[0:3], v207 offset1:1
	ds_read2st64_b64 v[4:7], v207 offset0:8 offset1:9
	v_mov_b32_e32 v152, v114
	s_waitcnt lgkmcnt(1)
	v_add_f32_e32 v0, 0, v0
	v_add_f32_e32 v1, 0, v1
	v_cndmask_b32_e64 v47, v1, 0, s[50:51]
	v_cndmask_b32_e64 v141, v0, 0, s[50:51]
	v_add_f32_e32 v144, v0, v2
	v_add_f32_e32 v145, v1, v3
	v_add_f32_e32 v0, v141, v2
	v_add_f32_e32 v1, v47, v3
	s_waitcnt lgkmcnt(0)
	v_add_f32_e32 v4, 0, v4
	v_add_f32_e32 v5, 0, v5
	v_cndmask_b32_e64 v47, v47, v1, s[52:53]
	v_cndmask_b32_e64 v141, v141, v0, s[52:53]
	v_add_f32_e32 v0, 0, v6
	v_add_f32_e32 v1, 0, v7
	v_add_f32_e32 v146, v4, v6
	v_add_f32_e32 v147, v5, v7
	v_cndmask_b32_e64 v148, 0, v1, s[50:51]
	v_cndmask_b32_e64 v149, 0, v0, s[50:51]
	ds_read2st64_b64 v[0:3], v207 offset0:2 offset1:3
	ds_read2st64_b64 v[4:7], v207 offset0:10 offset1:11
	s_waitcnt lgkmcnt(1)
	v_add_f32_e32 v144, v144, v0
	v_add_f32_e32 v145, v145, v1
	v_add_f32_e32 v0, v141, v0
	v_add_f32_e32 v1, v47, v1
	s_waitcnt lgkmcnt(0)
	v_add_f32_e32 v146, v146, v4
	v_add_f32_e32 v147, v147, v5
	v_cndmask_b32_e64 v1, v47, v1, s[48:49]
	v_cndmask_b32_e64 v0, v141, v0, s[48:49]
	v_add_f32_e32 v4, v149, v4
	v_add_f32_e32 v5, v148, v5
	v_cndmask_b32_e64 v5, 0, v5, s[46:47]
	v_cndmask_b32_e64 v4, 0, v4, s[46:47]
	v_add_f32_e32 v47, v144, v2
	v_add_f32_e32 v141, v145, v3
	v_add_f32_e32 v2, v0, v2
	v_add_f32_e32 v3, v1, v3
	v_add_f32_e32 v144, v146, v6
	v_add_f32_e32 v145, v147, v7
	v_cndmask_b32_e64 v146, v1, v3, s[44:45]
	v_cndmask_b32_e64 v147, v0, v2, s[44:45]
	v_add_f32_e32 v0, v4, v6
	v_add_f32_e32 v1, v5, v7
	v_cndmask_b32_e64 v148, 0, v1, s[42:43]
	v_cndmask_b32_e64 v149, 0, v0, s[42:43]
	ds_read2st64_b64 v[0:3], v207 offset0:4 offset1:5
	ds_read2st64_b64 v[4:7], v207 offset0:12 offset1:13
	s_waitcnt lgkmcnt(1)
	v_add_f32_e32 v47, v47, v0
	v_add_f32_e32 v141, v141, v1
	v_add_f32_e32 v0, v147, v0
	v_add_f32_e32 v1, v146, v1
	s_waitcnt lgkmcnt(0)
	v_add_f32_e32 v144, v144, v4
	v_add_f32_e32 v145, v145, v5
	v_cndmask_b32_e64 v1, v146, v1, s[40:41]
	v_cndmask_b32_e64 v0, v147, v0, s[40:41]
	v_add_f32_e32 v4, v149, v4
	v_add_f32_e32 v5, v148, v5
	v_cndmask_b32_e64 v5, 0, v5, s[38:39]
	v_cndmask_b32_e64 v4, 0, v4, s[38:39]
	v_add_f32_e32 v47, v47, v2
	v_add_f32_e32 v141, v141, v3
	v_add_f32_e32 v2, v0, v2
	v_add_f32_e32 v3, v1, v3
	v_cndmask_b32_e64 v147, v1, v3, s[36:37]
	v_cndmask_b32_e64 v148, v0, v2, s[36:37]
	v_add_f32_e32 v0, v4, v6
	v_add_f32_e32 v1, v5, v7
	v_add_f32_e32 v144, v144, v6
	v_add_f32_e32 v146, v145, v7
	v_cndmask_b32_e64 v149, 0, v1, s[34:35]
	v_cndmask_b32_e64 v150, 0, v0, s[34:35]
	ds_read2st64_b64 v[0:3], v207 offset0:6 offset1:7
	ds_read2st64_b64 v[4:7], v207 offset0:14 offset1:15
	s_waitcnt lgkmcnt(1)
	v_add_f32_e32 v145, v47, v0
	v_add_f32_e32 v0, v148, v0
	s_waitcnt lgkmcnt(0)
	v_add_f32_e32 v153, v144, v4
	v_cndmask_b32_e64 v47, v148, v0, s[30:31]
	v_add_f32_e32 v0, v150, v4
	v_add_f32_e32 v4, v149, v5
	v_add_f32_e32 v155, v141, v1
	v_add_f32_e32 v151, v146, v5
	v_add_f32_e32 v1, v147, v1
	v_cndmask_b32_e64 v5, 0, v4, s[28:29]
	v_cndmask_b32_e64 v1, v147, v1, s[30:31]
	v_add_f32_e32 v4, v47, v2
	v_add_f32_e32 v5, v5, v7
	v_cndmask_b32_e64 v141, 0, v0, s[28:29]
	v_add_f32_e32 v0, v1, v3
	v_cndmask_b32_e64 v4, v47, v4, s[26:27]
	v_cndmask_b32_e64 v146, 0, v5, s[24:25]
	v_mov_b32_e32 v144, v54
	v_mov_b32_e32 v5, v2
	v_cndmask_b32_e64 v0, v1, v0, s[26:27]
	v_add_f32_e32 v1, v141, v6
	v_pk_add_f32 v[144:145], v[144:145], v[4:5]
	v_cndmask_b32_e64 v148, 0, v1, s[24:25]
	v_sub_f32_e32 v5, v144, v145
	v_mov_b32_e32 v1, v3
	v_pk_add_f32 v[54:55], v[154:155], v[0:1]
	v_min_f32_e32 v47, 0x42a00000, v5
	v_sub_f32_e32 v1, v54, v55
	v_mul_f32_e32 v47, 0x3fb8aa3b, v47
	v_exp_f32_e32 v114, v47
	v_min_f32_e32 v47, 0x42a00000, v1
	v_mul_f32_e32 v47, 0x3fb8aa3b, v47
	v_mov_b32_e32 v150, v115
	v_exp_f32_e32 v115, v47
	v_mov_b32_e32 v149, v6
	v_pk_add_f32 v[2:3], v[152:153], v[148:149]
	v_mov_b32_e32 v147, v7
	v_pk_mul_f32 v[114:115], v[50:51], v[114:115]
	v_sub_f32_e32 v2, v2, v3
	v_cvt_pk_bf16_f32 v47, v114, v115
	v_pk_add_f32 v[6:7], v[150:151], v[146:147]
	global_store_dword v128, v47, s[58:59]
	v_min_f32_e32 v47, 0x42a00000, v2
	v_sub_f32_e32 v6, v6, v7
	v_mul_f32_e32 v47, 0x3fb8aa3b, v47
	v_exp_f32_e32 v114, v47
	v_min_f32_e32 v47, 0x42a00000, v6
	v_mul_f32_e32 v47, 0x3fb8aa3b, v47
	v_exp_f32_e32 v115, v47
	v_mul_f32_e32 v5, 0xbfb8aa3b, v5
	v_mul_f32_e32 v1, 0xbfb8aa3b, v1
	v_pk_mul_f32 v[50:51], v[50:51], v[114:115]
	s_nop 0
	v_cvt_pk_bf16_f32 v47, v50, v51
	v_exp_f32_e32 v50, v5
	v_exp_f32_e32 v51, v1
	v_add_f32_e32 v5, v122, v148
	v_sub_f32_e32 v5, v5, v3
	global_store_dword v128, v47, s[60:61]
	v_pk_mul_f32 v[50:51], v[52:53], v[50:51]
	s_nop 0
	v_cvt_pk_bf16_f32 v1, v50, v51
	global_store_dword v[44:45], v1, off offset:2048
	v_mul_f32_e32 v1, 0xbfb8aa3b, v2
	v_exp_f32_e32 v44, v1
	v_mul_f32_e32 v1, 0xbfb8aa3b, v6
	v_exp_f32_e32 v45, v1
	v_add_f32_e32 v2, v65, v0
	v_sub_f32_e32 v2, v2, v55
	v_add_f32_e32 v6, v123, v146
	v_pk_mul_f32 v[44:45], v[58:59], v[44:45]
	v_sub_f32_e32 v6, v6, v7
	v_cvt_pk_bf16_f32 v1, v44, v45
	global_store_dword v[42:43], v1, off
	v_add_f32_e32 v1, v64, v4
	v_sub_f32_e32 v1, v1, v145
	v_min_f32_e32 v42, 0x42a00000, v1
	v_min_f32_e32 v43, 0x42a00000, v2
	v_mul_f32_e32 v42, 0x3fb8aa3b, v42
	v_mul_f32_e32 v43, 0x3fb8aa3b, v43
	v_exp_f32_e32 v42, v42
	v_exp_f32_e32 v43, v43
	v_mul_f32_e32 v1, 0xbfb8aa3b, v1
	v_pk_mul_f32 v[42:43], v[56:57], v[42:43]
	s_nop 0
	v_cvt_pk_bf16_f32 v42, v42, v43
	global_store_dword v[40:41], v42, off offset:2048
	v_min_f32_e32 v40, 0x42a00000, v5
	v_min_f32_e32 v41, 0x42a00000, v6
	v_mul_f32_e32 v40, 0x3fb8aa3b, v40
	v_mul_f32_e32 v41, 0x3fb8aa3b, v41
	v_exp_f32_e32 v40, v40
	v_exp_f32_e32 v41, v41
	s_nop 0
	v_pk_mul_f32 v[40:41], v[56:57], v[40:41]
	s_nop 0
	v_cvt_pk_bf16_f32 v40, v40, v41
	global_store_dword v128, v40, s[60:61] offset:2048
	v_exp_f32_e32 v40, v1
	v_mul_f32_e32 v1, 0xbfb8aa3b, v2
	v_exp_f32_e32 v41, v1
	v_add_f32_e32 v2, v75, v0
	v_sub_f32_e32 v2, v2, v55
	v_pk_mul_f32 v[40:41], v[60:61], v[40:41]
	s_nop 0
	v_cvt_pk_bf16_f32 v1, v40, v41
	global_store_dword v[38:39], v1, off
	v_mul_f32_e32 v1, 0xbfb8aa3b, v5
	v_exp_f32_e32 v40, v1
	v_mul_f32_e32 v1, 0xbfb8aa3b, v6
	v_exp_f32_e32 v41, v1
	v_add_f32_e32 v5, v142, v148
	v_add_f32_e32 v6, v143, v146
	v_sub_f32_e32 v5, v5, v3
	v_pk_mul_f32 v[40:41], v[66:67], v[40:41]
	v_sub_f32_e32 v6, v6, v7
	v_cvt_pk_bf16_f32 v1, v40, v41
	global_store_dword v[38:39], v1, off offset:2048
	v_add_f32_e32 v1, v74, v4
	v_sub_f32_e32 v1, v1, v145
	v_min_f32_e32 v38, 0x42a00000, v1
	v_min_f32_e32 v39, 0x42a00000, v2
	v_mul_f32_e32 v38, 0x3fb8aa3b, v38
	v_mul_f32_e32 v39, 0x3fb8aa3b, v39
	v_exp_f32_e32 v38, v38
	v_exp_f32_e32 v39, v39
	v_mul_f32_e32 v1, 0xbfb8aa3b, v1
	v_pk_mul_f32 v[38:39], v[62:63], v[38:39]
	s_nop 0
	v_cvt_pk_bf16_f32 v38, v38, v39
	global_store_dword v[36:37], v38, off
	v_min_f32_e32 v36, 0x42a00000, v5
	v_min_f32_e32 v37, 0x42a00000, v6
	v_mul_f32_e32 v36, 0x3fb8aa3b, v36
	v_mul_f32_e32 v37, 0x3fb8aa3b, v37
	v_exp_f32_e32 v36, v36
	v_exp_f32_e32 v37, v37
	v_add_co_u32_e32 v38, vcc, s7, v48
	v_pk_mul_f32 v[36:37], v[62:63], v[36:37]
	s_nop 0
	v_addc_co_u32_e32 v39, vcc, 0, v49, vcc
	v_cvt_pk_bf16_f32 v40, v36, v37
	v_add_co_u32_e32 v36, vcc, s62, v48
	s_nop 1
	v_addc_co_u32_e32 v37, vcc, 0, v49, vcc
	global_store_dword v[36:37], v40, off offset:-4096
	v_exp_f32_e32 v40, v1
	v_mul_f32_e32 v1, 0xbfb8aa3b, v2
	v_exp_f32_e32 v41, v1
	v_add_f32_e32 v2, v81, v0
	v_sub_f32_e32 v2, v2, v55
	v_pk_mul_f32 v[40:41], v[68:69], v[40:41]
	s_nop 0
	v_cvt_pk_bf16_f32 v1, v40, v41
	global_store_dword v[34:35], v1, off offset:2048
	v_mul_f32_e32 v1, 0xbfb8aa3b, v5
	v_exp_f32_e32 v34, v1
	v_mul_f32_e32 v1, 0xbfb8aa3b, v6
	v_exp_f32_e32 v35, v1
	v_add_f32_e32 v5, v126, v148
	v_add_f32_e32 v6, v127, v146
	v_sub_f32_e32 v5, v5, v3
	v_pk_mul_f32 v[34:35], v[72:73], v[34:35]
	v_sub_f32_e32 v6, v6, v7
	v_cvt_pk_bf16_f32 v1, v34, v35
	global_store_dword v[30:31], v1, off
	v_add_f32_e32 v1, v80, v4
	v_sub_f32_e32 v1, v1, v145
	v_min_f32_e32 v30, 0x42a00000, v1
	v_min_f32_e32 v31, 0x42a00000, v2
	v_mul_f32_e32 v30, 0x3fb8aa3b, v30
	v_mul_f32_e32 v31, 0x3fb8aa3b, v31
	v_exp_f32_e32 v30, v30
	v_exp_f32_e32 v31, v31
	v_mul_f32_e32 v1, 0xbfb8aa3b, v1
	v_pk_mul_f32 v[30:31], v[70:71], v[30:31]
	s_nop 0
	v_cvt_pk_bf16_f32 v30, v30, v31
	global_store_dword v[32:33], v30, off offset:2048
	v_min_f32_e32 v30, 0x42a00000, v5
	v_min_f32_e32 v31, 0x42a00000, v6
	v_mul_f32_e32 v30, 0x3fb8aa3b, v30
	v_mul_f32_e32 v31, 0x3fb8aa3b, v31
	v_exp_f32_e32 v30, v30
	v_exp_f32_e32 v31, v31
	s_nop 0
	v_pk_mul_f32 v[30:31], v[70:71], v[30:31]
	s_nop 0
	v_cvt_pk_bf16_f32 v30, v30, v31
	global_store_dword v[38:39], v30, off offset:2048
	v_exp_f32_e32 v30, v1
	v_mul_f32_e32 v1, 0xbfb8aa3b, v2
	v_exp_f32_e32 v31, v1
	v_add_f32_e32 v2, v89, v0
	v_sub_f32_e32 v2, v2, v55
	v_pk_mul_f32 v[30:31], v[76:77], v[30:31]
	s_nop 0
	v_cvt_pk_bf16_f32 v1, v30, v31
	global_store_dword v[28:29], v1, off
	v_mul_f32_e32 v1, 0xbfb8aa3b, v5
	v_exp_f32_e32 v30, v1
	v_mul_f32_e32 v1, 0xbfb8aa3b, v6
	v_exp_f32_e32 v31, v1
	v_add_f32_e32 v5, v124, v148
	v_add_f32_e32 v6, v125, v146
	v_sub_f32_e32 v5, v5, v3
	v_pk_mul_f32 v[30:31], v[82:83], v[30:31]
	v_sub_f32_e32 v6, v6, v7
	v_cvt_pk_bf16_f32 v1, v30, v31
	global_store_dword v[28:29], v1, off offset:2048
	v_add_f32_e32 v1, v88, v4
	v_sub_f32_e32 v1, v1, v145
	v_min_f32_e32 v28, 0x42a00000, v1
	v_min_f32_e32 v29, 0x42a00000, v2
	v_mul_f32_e32 v28, 0x3fb8aa3b, v28
	v_mul_f32_e32 v29, 0x3fb8aa3b, v29
	v_exp_f32_e32 v28, v28
	v_exp_f32_e32 v29, v29
	v_mul_f32_e32 v1, 0xbfb8aa3b, v1
	v_pk_mul_f32 v[28:29], v[78:79], v[28:29]
	s_nop 0
	v_cvt_pk_bf16_f32 v28, v28, v29
	global_store_dword v[26:27], v28, off
	v_min_f32_e32 v26, 0x42a00000, v5
	v_min_f32_e32 v27, 0x42a00000, v6
	v_mul_f32_e32 v26, 0x3fb8aa3b, v26
	v_mul_f32_e32 v27, 0x3fb8aa3b, v27
	v_exp_f32_e32 v26, v26
	v_exp_f32_e32 v27, v27
	s_nop 0
	v_pk_mul_f32 v[26:27], v[78:79], v[26:27]
	s_nop 0
	v_cvt_pk_bf16_f32 v26, v26, v27
	global_store_dword v[36:37], v26, off
	v_exp_f32_e32 v26, v1
	v_mul_f32_e32 v1, 0xbfb8aa3b, v2
	v_exp_f32_e32 v27, v1
	v_add_f32_e32 v2, v97, v0
	v_sub_f32_e32 v2, v2, v55
	v_pk_mul_f32 v[26:27], v[84:85], v[26:27]
	s_nop 0
	v_cvt_pk_bf16_f32 v1, v26, v27
	global_store_dword v[24:25], v1, off offset:2048
	v_mul_f32_e32 v1, 0xbfb8aa3b, v5
	v_exp_f32_e32 v24, v1
	v_mul_f32_e32 v1, 0xbfb8aa3b, v6
	v_exp_f32_e32 v25, v1
	v_add_f32_e32 v5, v120, v148
	v_add_f32_e32 v6, v121, v146
	v_sub_f32_e32 v5, v5, v3
	v_pk_mul_f32 v[24:25], v[90:91], v[24:25]
	v_sub_f32_e32 v6, v6, v7
	v_cvt_pk_bf16_f32 v1, v24, v25
	global_store_dword v[22:23], v1, off
	v_add_f32_e32 v1, v96, v4
	v_sub_f32_e32 v1, v1, v145
	v_min_f32_e32 v22, 0x42a00000, v1
	v_min_f32_e32 v23, 0x42a00000, v2
	v_mul_f32_e32 v22, 0x3fb8aa3b, v22
	v_mul_f32_e32 v23, 0x3fb8aa3b, v23
	v_exp_f32_e32 v22, v22
	v_exp_f32_e32 v23, v23
	v_mul_f32_e32 v1, 0xbfb8aa3b, v1
	v_pk_mul_f32 v[22:23], v[86:87], v[22:23]
	s_nop 0
	v_cvt_pk_bf16_f32 v22, v22, v23
	global_store_dword v[20:21], v22, off offset:2048
	v_min_f32_e32 v20, 0x42a00000, v5
	v_min_f32_e32 v21, 0x42a00000, v6
	v_mul_f32_e32 v20, 0x3fb8aa3b, v20
	v_mul_f32_e32 v21, 0x3fb8aa3b, v21
	v_exp_f32_e32 v20, v20
	v_exp_f32_e32 v21, v21
	s_nop 0
	v_pk_mul_f32 v[20:21], v[86:87], v[20:21]
	s_nop 0
	v_cvt_pk_bf16_f32 v20, v20, v21
	global_store_dword v[36:37], v20, off offset:2048
	v_exp_f32_e32 v20, v1
	v_mul_f32_e32 v1, 0xbfb8aa3b, v2
	v_exp_f32_e32 v21, v1
	v_add_f32_e32 v2, v107, v0
	v_sub_f32_e32 v2, v2, v55
	v_add_f32_e32 v0, v111, v0
	v_pk_mul_f32 v[20:21], v[92:93], v[20:21]
	s_nop 0
	v_cvt_pk_bf16_f32 v1, v20, v21
	global_store_dword v[16:17], v1, off
	v_mul_f32_e32 v1, 0xbfb8aa3b, v5
	v_exp_f32_e32 v20, v1
	v_mul_f32_e32 v1, 0xbfb8aa3b, v6
	v_exp_f32_e32 v21, v1
	v_add_f32_e32 v5, v118, v148
	v_add_f32_e32 v6, v119, v146
	v_sub_f32_e32 v5, v5, v3
	v_pk_mul_f32 v[20:21], v[98:99], v[20:21]
	v_sub_f32_e32 v6, v6, v7
	v_cvt_pk_bf16_f32 v1, v20, v21
	global_store_dword v[16:17], v1, off offset:2048
	v_add_f32_e32 v1, v106, v4
	v_sub_f32_e32 v1, v1, v145
	v_min_f32_e32 v16, 0x42a00000, v1
	v_min_f32_e32 v17, 0x42a00000, v2
	v_mul_f32_e32 v16, 0x3fb8aa3b, v16
	v_mul_f32_e32 v17, 0x3fb8aa3b, v17
	v_exp_f32_e32 v16, v16
	v_exp_f32_e32 v17, v17
	v_mul_f32_e32 v1, 0xbfb8aa3b, v1
	v_pk_mul_f32 v[16:17], v[94:95], v[16:17]
	s_nop 0
	v_cvt_pk_bf16_f32 v16, v16, v17
	global_store_dword v[18:19], v16, off
	v_min_f32_e32 v16, 0x42a00000, v5
	v_min_f32_e32 v17, 0x42a00000, v6
	v_mul_f32_e32 v16, 0x3fb8aa3b, v16
	v_mul_f32_e32 v17, 0x3fb8aa3b, v17
	v_exp_f32_e32 v16, v16
	v_exp_f32_e32 v17, v17
	s_nop 0
	v_pk_mul_f32 v[16:17], v[94:95], v[16:17]
	s_nop 0
	v_cvt_pk_bf16_f32 v18, v16, v17
	v_add_co_u32_e32 v16, vcc, s63, v48
	s_nop 1
	v_addc_co_u32_e32 v17, vcc, 0, v49, vcc
	global_store_dword v[16:17], v18, off
	v_exp_f32_e32 v18, v1
	v_mul_f32_e32 v1, 0xbfb8aa3b, v2
	v_exp_f32_e32 v19, v1
	s_nop 0
	v_pk_mul_f32 v[18:19], v[100:101], v[18:19]
	s_nop 0
	v_cvt_pk_bf16_f32 v1, v18, v19
	global_store_dword v[14:15], v1, off offset:2048
	v_mul_f32_e32 v1, 0xbfb8aa3b, v5
	v_exp_f32_e32 v14, v1
	v_mul_f32_e32 v1, 0xbfb8aa3b, v6
	v_exp_f32_e32 v15, v1
	s_nop 0
	v_pk_mul_f32 v[14:15], v[104:105], v[14:15]
	s_nop 0
	v_cvt_pk_bf16_f32 v1, v14, v15
	global_store_dword v[12:13], v1, off
	v_add_f32_e32 v1, v110, v4
	v_sub_f32_e32 v4, v0, v55
	v_add_f32_e32 v0, v116, v148
	v_sub_f32_e32 v2, v1, v145
	v_sub_f32_e32 v5, v0, v3
	v_add_f32_e32 v0, v117, v146
	v_sub_f32_e32 v6, v0, v7
	v_min_f32_e32 v0, 0x42a00000, v2
	v_min_f32_e32 v1, 0x42a00000, v4
	v_mul_f32_e32 v0, 0x3fb8aa3b, v0
	v_mul_f32_e32 v1, 0x3fb8aa3b, v1
	v_exp_f32_e32 v0, v0
	v_exp_f32_e32 v1, v1
	s_nop 0
	v_pk_mul_f32 v[0:1], v[102:103], v[0:1]
	s_nop 0
	v_cvt_pk_bf16_f32 v0, v0, v1
	global_store_dword v[10:11], v0, off offset:2048
	v_min_f32_e32 v0, 0x42a00000, v5
	v_min_f32_e32 v1, 0x42a00000, v6
	v_mul_f32_e32 v0, 0x3fb8aa3b, v0
	v_mul_f32_e32 v1, 0x3fb8aa3b, v1
	v_exp_f32_e32 v0, v0
	v_exp_f32_e32 v1, v1
	s_nop 0
	v_pk_mul_f32 v[0:1], v[102:103], v[0:1]
	s_nop 0
	v_cvt_pk_bf16_f32 v0, v0, v1
	global_store_dword v[16:17], v0, off offset:2048
	v_mul_f32_e32 v0, 0xbfb8aa3b, v2
	v_mul_f32_e32 v1, 0xbfb8aa3b, v4
	v_exp_f32_e32 v0, v0
	v_exp_f32_e32 v1, v1
	s_nop 0
	v_pk_mul_f32 v[0:1], v[108:109], v[0:1]
	s_nop 0
	v_cvt_pk_bf16_f32 v0, v0, v1
	global_store_dword v[8:9], v0, off
	v_mul_f32_e32 v0, 0xbfb8aa3b, v5
	v_mul_f32_e32 v1, 0xbfb8aa3b, v6
	v_exp_f32_e32 v0, v0
	v_exp_f32_e32 v1, v1
	s_nop 0
	v_pk_mul_f32 v[0:1], v[112:113], v[0:1]
	s_nop 0
	v_cvt_pk_bf16_f32 v0, v0, v1
	global_store_dword v[8:9], v0, off offset:2048
	s_cbranch_scc1 .LBB0_394
	s_lshl_b32 s12, s56, 1
	s_ashr_i32 s13, s12, 31
	s_lshl_b64 s[12:13], s[12:13], 18
	s_add_u32 s9, s84, s12
	s_addc_u32 s12, s85, s13
	s_lshl_b32 s8, s8, 12
	v_mul_f32_e32 v0, 0x3fb8aa3b, v145
	v_mul_f32_e32 v1, 0x3fb8aa3b, v55
	s_add_u32 s8, s9, s8
	v_exp_f32_e32 v0, v0
	v_exp_f32_e32 v1, v1
	s_addc_u32 s9, s12, 0
	s_add_u32 s8, s8, s0
	s_addc_u32 s9, s9, 0
	global_store_dwordx2 v46, v[0:1], s[8:9]
	v_mul_f32_e32 v0, 0x3fb8aa3b, v3
	v_mul_f32_e32 v1, 0x3fb8aa3b, v7
	v_mov_b32_e32 v47, v129
	v_exp_f32_e32 v0, v0
	v_exp_f32_e32 v1, v1
	v_lshl_add_u64 v[4:5], s[8:9], 0, v[46:47]
	v_add_co_u32_e32 v2, vcc, 0x40000, v4
	s_nop 1
	v_addc_co_u32_e32 v3, vcc, 0, v5, vcc
	global_store_dwordx2 v[2:3], v[0:1], off
	s_branch .LBB0_394
